# baseline (speedup 1.0000x reference)
.LBB0_672:
	ds_read_b128 v[34:37], v169 offset:24576
	ds_read_b128 v[38:41], v169 offset:28672
	ds_read_b128 v[194:197], v168 offset:24576
	ds_read_b128 v[198:201], v168 offset:28672
	ds_read_b128 v[214:217], v166 offset:24576
	ds_read_b128 v[218:221], v166 offset:28672
	ds_read_b128 v[222:225], v191 offset:24576
	ds_read_b128 v[226:229], v191 offset:28672
	v_exp_f32_e32 v128, v128
	v_exp_f32_e32 v129, v129
	s_waitcnt lgkmcnt(7)
	v_mfma_f32_32x32x16_bf16 v[50:65], v[34:37], v[78:81], 0
	v_exp_f32_e32 v158, v160
	v_exp_f32_e32 v159, v161
	v_exp_f32_e32 v160, v120
	v_exp_f32_e32 v161, v121
	v_exp_f32_e32 v180, v122
	v_exp_f32_e32 v181, v123
	v_exp_f32_e32 v182, v124
	s_waitcnt lgkmcnt(6)
	v_mfma_f32_32x32x16_bf16 v[34:49], v[38:41], v[78:81], 0
	v_exp_f32_e32 v183, v125
	v_cvt_pk_bf16_f32 v120, v98, v99
	v_cvt_pk_bf16_f32 v121, v100, v101
	v_cvt_pk_bf16_f32 v122, v104, v105
	v_cvt_pk_bf16_f32 v123, v102, v103
	v_cvt_pk_bf16_f32 v124, v128, v129
	v_cvt_pk_bf16_f32 v125, v158, v159
	s_waitcnt lgkmcnt(4)
	v_mfma_f32_32x32x16_bf16 v[34:49], v[198:201], v[66:69], v[34:49]
	v_permlane32_swap_b32_e32 v120, v122
	v_permlane32_swap_b32_e32 v121, v123
	v_mfma_f32_32x32x16_bf16 v[50:65], v[194:197], v[66:69], v[50:65]
	s_waitcnt lgkmcnt(2)
	v_mfma_f32_32x32x16_bf16 v[34:49], v[218:221], v[70:73], v[34:49]
	v_mfma_f32_32x32x16_bf16 v[50:65], v[214:217], v[70:73], v[50:65]
	s_waitcnt lgkmcnt(0)
	v_mfma_f32_32x32x16_bf16 v[34:49], v[226:229], v[74:77], v[34:49]
	v_exp_f32_e32 v198, v116
	v_exp_f32_e32 v199, v117
	v_pk_add_f32 v[116:117], v[106:107], 0 op_sel_hi:[1,0]
	v_exp_f32_e32 v200, v118
	v_pk_add_f32 v[116:117], v[108:109], v[116:117]
	v_exp_f32_e32 v201, v119
	v_pk_add_f32 v[116:117], v[110:111], v[116:117]
	v_mfma_f32_32x32x16_bf16 v[50:65], v[222:225], v[74:77], v[50:65]
	v_add_f32_e64 v116, v112, v116
	v_add_f32_e64 v117, v113, v117
	v_exp_f32_e32 v196, v126
	v_pk_add_f32 v[116:117], v[98:99], v[116:117]
	v_exp_f32_e32 v197, v127
	v_pk_add_f32 v[116:117], v[100:101], v[116:117]
	v_cvt_pk_bf16_f32 v118, v110, v111
	v_cvt_pk_bf16_f32 v119, v112, v113
	v_cvt_pk_bf16_f32 v126, v160, v161
	v_cvt_pk_bf16_f32 v127, v180, v181
	s_nop 0
	v_pk_add_f32 v[116:117], v[104:105], v[116:117]
	v_permlane32_swap_b32_e32 v124, v126
	v_pk_add_f32 v[116:117], v[102:103], v[116:117]
	v_permlane32_swap_b32_e32 v125, v127
	v_pk_add_f32 v[116:117], v[128:129], v[116:117]
	s_nop 0
	v_pk_add_f32 v[116:117], v[158:159], v[116:117]
	v_cvt_pk_bf16_f32 v158, v182, v183
	v_cvt_pk_bf16_f32 v159, v196, v197
	s_nop 0
	v_pk_add_f32 v[116:117], v[160:161], v[116:117]
	v_cvt_pk_bf16_f32 v160, v198, v199
	v_cvt_pk_bf16_f32 v161, v200, v201
	s_nop 0
	v_pk_add_f32 v[116:117], v[180:181], v[116:117]
	v_permlane32_swap_b32_e32 v158, v160
	v_pk_add_f32 v[116:117], v[182:183], v[116:117]
	v_permlane32_swap_b32_e32 v159, v161
	v_pk_add_f32 v[116:117], v[196:197], v[116:117]
	s_nop 0
	v_pk_add_f32 v[116:117], v[198:199], v[116:117]
	s_nop 0
	v_pk_add_f32 v[116:117], v[200:201], v[116:117]
	s_nop 0
	v_pk_add_f32 v[144:145], v[116:117], v[116:117] op_sel:[0,1] op_sel_hi:[1,0]
	v_cvt_pk_bf16_f32 v116, v106, v107
	v_cvt_pk_bf16_f32 v117, v108, v109
	s_nop 0
	v_mov_b32_e32 v194, v144
	s_nop 1
	v_permlane32_swap_b32_e32 v144, v194
	v_permlane32_swap_b32_e32 v116, v118
	v_permlane32_swap_b32_e32 v117, v119
	s_mov_b32 s4, 0xfff87f00
	v_add_co_u32_e32 v102, vcc, s4, v142
	s_mov_b32 s4, 0xfffaff00
	s_nop 0
	v_addc_co_u32_e32 v103, vcc, -1, v143, vcc
	v_add_co_u32_e32 v106, vcc, s4, v142
	s_nop 1
	v_addc_co_u32_e32 v107, vcc, -1, v143, vcc
	flat_load_dwordx4 v[98:101], v[102:103] offset:256
	s_nop 0
	flat_load_dwordx4 v[102:105], v[102:103]
	s_nop 0
	flat_load_dwordx4 v[110:113], v[106:107] offset:256
	s_nop 0
	flat_load_dwordx4 v[106:109], v[106:107]
	ds_read_b64_tr_b16 v[196:197], v162 offset:0
	ds_read_b64_tr_b16 v[198:199], v162 offset:0x400
	ds_read_b64_tr_b16 v[200:201], v162 offset:0x800
	ds_read_b64_tr_b16 v[202:203], v162 offset:0xc00
	ds_read_b64_tr_b16 v[204:205], v162 offset:0x1000
	ds_read_b64_tr_b16 v[206:207], v162 offset:0x1400
	ds_read_b64_tr_b16 v[208:209], v162 offset:0x1800
	ds_read_b64_tr_b16 v[210:211], v162 offset:0x1c00
	s_waitcnt lgkmcnt(0)
	s_nop 0
	v_mfma_f32_32x32x16_bf16 v[2:17], v[116:119], v[196:199], v[2:17]
	ds_read_b64_tr_b16 v[196:197], v162 offset:0x200
	ds_read_b64_tr_b16 v[198:199], v162 offset:0x600
	v_mfma_f32_32x32x16_bf16 v[2:17], v[120:123], v[200:203], v[2:17]
	ds_read_b64_tr_b16 v[200:201], v162 offset:0xa00
	ds_read_b64_tr_b16 v[202:203], v162 offset:0xe00
	v_mfma_f32_32x32x16_bf16 v[2:17], v[124:127], v[204:207], v[2:17]
	ds_read_b64_tr_b16 v[204:205], v162 offset:0x1200
	ds_read_b64_tr_b16 v[206:207], v162 offset:0x1600
	v_mfma_f32_32x32x16_bf16 v[2:17], v[158:161], v[208:211], v[2:17]
	ds_read_b64_tr_b16 v[208:209], v162 offset:0x1a00
	ds_read_b64_tr_b16 v[210:211], v162 offset:0x1e00
	s_waitcnt lgkmcnt(0)
	v_mfma_f32_32x32x16_bf16 v[18:33], v[116:119], v[196:199], v[18:33]
	v_max_f32_e32 v115, v51, v51
	v_max_f32_e32 v116, v50, v50
	v_max_f32_e32 v115, v116, v115
	v_max3_f32 v115, v115, v52, v53
	v_max3_f32 v115, v115, v54, v55
	v_max3_f32 v115, v115, v56, v57
	v_max3_f32 v115, v115, v58, v59
	v_mfma_f32_32x32x16_bf16 v[18:33], v[120:123], v[200:203], v[18:33]
	v_max3_f32 v115, v115, v60, v61
	v_max3_f32 v115, v115, v62, v63
	v_max3_f32 v115, v115, v64, v65
	v_max3_f32 v115, v115, v34, v35
	v_max3_f32 v115, v115, v36, v37
	v_max3_f32 v115, v115, v38, v39
	v_max3_f32 v115, v115, v40, v41
	v_mfma_f32_32x32x16_bf16 v[18:33], v[124:127], v[204:207], v[18:33]
	v_max3_f32 v115, v115, v42, v43
	v_max3_f32 v115, v115, v44, v45
	v_max3_f32 v115, v115, v46, v47
	v_max3_f32 v115, v115, v48, v49
	v_mov_b32_e32 v116, v115
	s_nop 1
	v_permlane32_swap_b32_e32 v115, v116
	v_mfma_f32_32x32x16_bf16 v[18:33], v[158:161], v[208:211], v[18:33]
	v_max_f32_e32 v116, v116, v116
	v_max_f32_e32 v115, v115, v115
	v_max_f32_e32 v115, v115, v116
	v_sub_f32_e32 v116, v115, v114
	v_cmp_ge_f32_e32 vcc, s0, v116
	s_cmp_lg_u64 vcc, exec
	s_cbranch_scc1 .LBB0_687
	v_mov_b32_e32 v116, v114

.LBB0_679:
	v_mov_b32_e32 v117, v116
	v_pk_add_f32 v[50:51], v[50:51], v[116:117] op_sel_hi:[1,0] neg_lo:[0,1] neg_hi:[0,1]
	v_pk_add_f32 v[158:159], v[34:35], v[116:117] neg_lo:[0,1] neg_hi:[0,1]
	v_exp_f32_e32 v114, v50
	v_exp_f32_e32 v115, v51
	v_pk_add_f32 v[50:51], v[52:53], v[116:117] op_sel_hi:[1,0] neg_lo:[0,1] neg_hi:[0,1]
	v_pk_add_f32 v[180:181], v[36:37], v[116:117] neg_lo:[0,1] neg_hi:[0,1]
	v_exp_f32_e32 v124, v50
	v_exp_f32_e32 v125, v51
	v_pk_add_f32 v[50:51], v[54:55], v[116:117] op_sel_hi:[1,0] neg_lo:[0,1] neg_hi:[0,1]
	v_pk_add_f32 v[182:183], v[38:39], v[116:117] neg_lo:[0,1] neg_hi:[0,1]
	v_exp_f32_e32 v128, v50
	v_exp_f32_e32 v129, v51
	v_pk_add_f32 v[50:51], v[56:57], v[116:117] op_sel_hi:[1,0] neg_lo:[0,1] neg_hi:[0,1]
	v_pk_add_f32 v[206:207], v[40:41], v[116:117] neg_lo:[0,1] neg_hi:[0,1]
	v_exp_f32_e32 v160, v50
	v_exp_f32_e32 v161, v51
	v_pk_add_f32 v[50:51], v[58:59], v[116:117] op_sel_hi:[1,0] neg_lo:[0,1] neg_hi:[0,1]
	v_pk_add_f32 v[208:209], v[42:43], v[116:117] neg_lo:[0,1] neg_hi:[0,1]
	v_exp_f32_e32 v118, v50
	v_exp_f32_e32 v119, v51
	v_pk_add_f32 v[50:51], v[60:61], v[116:117] op_sel_hi:[1,0] neg_lo:[0,1] neg_hi:[0,1]
	v_pk_add_f32 v[210:211], v[44:45], v[116:117] neg_lo:[0,1] neg_hi:[0,1]
	v_exp_f32_e32 v120, v50
	v_exp_f32_e32 v121, v51
	v_pk_add_f32 v[50:51], v[62:63], v[116:117] op_sel_hi:[1,0] neg_lo:[0,1] neg_hi:[0,1]
	v_pk_add_f32 v[212:213], v[46:47], v[116:117] neg_lo:[0,1] neg_hi:[0,1]
	v_exp_f32_e32 v126, v50
	v_exp_f32_e32 v127, v51
	v_pk_add_f32 v[50:51], v[64:65], v[116:117] op_sel_hi:[1,0] neg_lo:[0,1] neg_hi:[0,1]
	v_pk_add_f32 v[116:117], v[48:49], v[116:117] neg_lo:[0,1] neg_hi:[0,1]
	v_exp_f32_e32 v122, v50
	v_exp_f32_e32 v123, v51
	s_waitcnt lgkmcnt(0)
	s_barrier
	ds_read_b128 v[34:37], v169 offset:16384
	ds_read_b128 v[38:41], v169 offset:20480
	ds_read_b128 v[198:201], v168 offset:16384
	ds_read_b128 v[202:205], v168 offset:20480
	ds_read_b128 v[214:217], v166 offset:16384
	ds_read_b128 v[218:221], v166 offset:20480
	ds_read_b128 v[222:225], v191 offset:16384
	ds_read_b128 v[226:229], v191 offset:20480
	v_exp_f32_e32 v180, v180
	v_exp_f32_e32 v181, v181
	s_waitcnt lgkmcnt(4)
	v_mfma_f32_32x32x16_bf16 v[50:65], v[34:37], v[78:81], 0
	v_exp_f32_e32 v182, v182
	v_exp_f32_e32 v183, v183
	v_mfma_f32_32x32x16_bf16 v[34:49], v[38:41], v[78:81], 0
	v_mfma_f32_32x32x16_bf16 v[34:49], v[202:205], v[66:69], v[34:49]
	v_mfma_f32_32x32x16_bf16 v[50:65], v[198:201], v[66:69], v[50:65]
	s_waitcnt lgkmcnt(2)
	v_mfma_f32_32x32x16_bf16 v[34:49], v[218:221], v[70:73], v[34:49]
	v_mfma_f32_32x32x16_bf16 v[50:65], v[214:217], v[70:73], v[50:65]
	s_waitcnt lgkmcnt(0)
	v_mfma_f32_32x32x16_bf16 v[34:49], v[226:229], v[74:77], v[34:49]
	v_exp_f32_e32 v202, v208
	v_exp_f32_e32 v203, v209
	v_exp_f32_e32 v208, v116
	v_exp_f32_e32 v209, v117
	v_pk_add_f32 v[116:117], v[114:115], 0 op_sel_hi:[1,0]
	v_exp_f32_e32 v204, v210
	v_pk_add_f32 v[116:117], v[124:125], v[116:117]
	v_mfma_f32_32x32x16_bf16 v[50:65], v[222:225], v[74:77], v[50:65]
	v_add_f32_e64 v116, v128, v116
	v_add_f32_e64 v117, v129, v117
	v_exp_f32_e32 v198, v158
	v_pk_add_f32 v[116:117], v[160:161], v[116:117]
	v_exp_f32_e32 v199, v159
	v_pk_add_f32 v[116:117], v[118:119], v[116:117]
	v_exp_f32_e32 v200, v206
	v_pk_add_f32 v[116:117], v[120:121], v[116:117]
	v_exp_f32_e32 v201, v207
	v_pk_add_f32 v[116:117], v[126:127], v[116:117]
	v_exp_f32_e32 v205, v211
	v_pk_add_f32 v[116:117], v[122:123], v[116:117]
	v_exp_f32_e32 v206, v212
	v_pk_add_f32 v[116:117], v[198:199], v[116:117]
	v_exp_f32_e32 v207, v213
	v_pk_add_f32 v[116:117], v[180:181], v[116:117]
	v_cvt_pk_bf16_f32 v114, v114, v115
	v_cvt_pk_bf16_f32 v115, v124, v125
	v_cvt_pk_bf16_f32 v118, v118, v119
	v_cvt_pk_bf16_f32 v119, v120, v121
	v_cvt_pk_bf16_f32 v120, v126, v127
	s_nop 0
	v_pk_add_f32 v[116:117], v[182:183], v[116:117]
	v_cvt_pk_bf16_f32 v121, v122, v123
	v_cvt_pk_bf16_f32 v122, v198, v199
	v_cvt_pk_bf16_f32 v123, v180, v181
	v_cvt_pk_bf16_f32 v124, v182, v183
	v_cvt_pk_bf16_f32 v125, v200, v201
	s_nop 0
	v_pk_add_f32 v[116:117], v[200:201], v[116:117]
	v_cvt_pk_bf16_f32 v126, v202, v203
	v_cvt_pk_bf16_f32 v127, v204, v205
	v_permlane32_swap_b32_e32 v118, v120
	v_pk_add_f32 v[116:117], v[202:203], v[116:117]
	v_permlane32_swap_b32_e32 v119, v121
	v_pk_add_f32 v[116:117], v[204:205], v[116:117]
	v_permlane32_swap_b32_e32 v122, v124
	v_pk_add_f32 v[116:117], v[206:207], v[116:117]
	v_permlane32_swap_b32_e32 v123, v125
	v_pk_add_f32 v[116:117], v[208:209], v[116:117]
	s_nop 0
	v_pk_add_f32 v[158:159], v[116:117], v[116:117] op_sel:[0,1] op_sel_hi:[1,0]
	v_cvt_pk_bf16_f32 v116, v128, v129
	v_cvt_pk_bf16_f32 v117, v160, v161
	v_cvt_pk_bf16_f32 v128, v206, v207
	v_cvt_pk_bf16_f32 v129, v208, v209
	s_nop 0
	v_mov_b32_e32 v159, v158
	s_nop 1
	v_permlane32_swap_b32_e32 v158, v159
	v_permlane32_swap_b32_e32 v114, v116
	v_permlane32_swap_b32_e32 v115, v117
	v_permlane32_swap_b32_e32 v126, v128
	v_permlane32_swap_b32_e32 v127, v129
	v_cmp_lt_u32_e32 vcc, s30, v157
	s_and_saveexec_b64 s[22:23], vcc
	s_cbranch_execz .LBB0_681
	v_add_co_u32_e32 v82, vcc, 0xfffd8000, v142
	s_nop 1
	v_addc_co_u32_e32 v83, vcc, -1, v143, vcc
	v_add_co_u32_e32 v84, vcc, 0xfffd7f00, v142
	s_nop 1
	v_addc_co_u32_e32 v85, vcc, -1, v143, vcc
	v_add_co_u32_e32 v90, vcc, 0xffffff00, v142
	flat_load_dwordx4 v[86:89], v[82:83]
	s_nop 0
	flat_load_dwordx4 v[82:85], v[84:85]
	v_addc_co_u32_e32 v91, vcc, -1, v143, vcc
	flat_load_dwordx4 v[94:97], v[142:143]
	s_nop 0
	flat_load_dwordx4 v[90:93], v[90:91]
